# overlay-epoch seams (out-proj->MLP-in, end of layer) become split barriers in local mode: XCC leader flushes and signals arrival, waves wait for all XCCs only before the first conflicting epilogue sto
# speedup vs baseline: 1.0113x; 1.0113x over previous
; #define LAS __attribute__((address_space(3)))
; __global__ void __launch_bounds__(512) fwd_megakernel(KArgs a) {
;     ...
;     const int wave = __builtin_amdgcn_readfirstlane(threadIdx.x >> 6);
;     const int G = gridDim.x, bx = blockIdx.x;
;     volatile LAS unsigned* MISC = (volatile LAS unsigned*)(lds + 131072);
;     if (threadIdx.x < 16) MISC[threadIdx.x] = 0u;
;     __syncthreads();
;     XcdBarrier xbar = xcd_barrier_post((unsigned*)(a.ws + WS_CTL), MISC + 8);
_Z14fwd_megakernel5KArgs:
	s_load_dwordx2 s[68:69], s[0:1], 0xb0
	s_load_dwordx4 s[4:7], s[0:1], 0xa0
	s_load_dword s71, s[0:1], 0xc8
	s_load_dwordx2 s[84:85], s[0:1], 0xc0
	v_and_b32_e32 v202, 0x3ff, v0
	v_cmp_gt_u32_e32 vcc, 16, v202
	s_waitcnt lgkmcnt(0)
	v_writelane_b32 v252, s4, 0
	s_nop 1
	v_writelane_b32 v252, s5, 1
	v_writelane_b32 v252, s6, 2
	v_writelane_b32 v252, s7, 3
	s_load_dwordx8 s[4:11], s[0:1], 0x80
	s_waitcnt lgkmcnt(0)
	v_writelane_b32 v252, s4, 4
	s_nop 1
	v_writelane_b32 v252, s5, 5
	v_writelane_b32 v252, s6, 6
	v_writelane_b32 v252, s7, 7
	v_writelane_b32 v252, s8, 8
	v_writelane_b32 v252, s9, 9
	v_writelane_b32 v252, s10, 10
	v_writelane_b32 v252, s11, 11
	s_add_u32 s8, s0, 0xc0
	s_addc_u32 s9, s1, 0
	v_readfirstlane_b32 s10, v202
	s_and_saveexec_b64 s[4:5], vcc
	v_lshl_add_u32 v1, v202, 2, 0
	v_add_u32_e32 v1, 0x20000, v1
	v_mov_b32_e32 v2, 0
	ds_write_b32 v1, v2
	s_or_b64 exec, exec, s[4:5]
	s_waitcnt lgkmcnt(0)
	s_barrier
	s_add_u32 s26, s68, 0xb00000
	s_getreg_b32 s3, hwreg(HW_REG_XCC_ID, 0, 4)
	s_addc_u32 s27, s69, 0
	s_and_b32 s73, s3, 15
	v_cmp_eq_u32_e64 s[96:97], 0, v202
	s_and_saveexec_b64 s[4:5], s[96:97]
	s_cbranch_execz .LBB0_5
	s_mov_b64 s[6:7], exec
	v_mbcnt_lo_u32_b32 v1, s6, 0
	v_mbcnt_hi_u32_b32 v1, s7, v1
	v_cmp_eq_u32_e32 vcc, 0, v1
	s_and_b64 s[12:13], exec, vcc
	s_mov_b64 exec, s[12:13]
	s_cbranch_execz .LBB0_5
	s_lshl_b32 s3, s73, 8
	s_bcnt1_i32_b64 s6, s[6:7]
	v_mov_b32_e32 v1, s3
	v_mov_b32_e32 v2, s6
	global_atomic_add v1, v2, s[26:27] offset:1024
	s_and_b32 s3, s2, 7
	s_lshl_b32 s3, s3, 4
	s_add_i32 s3, s3, s73
	s_lshl_b32 s3, s3, 2
	s_add_i32 s3, s3, 0x4000
	v_mov_b32_e32 v1, s3
	v_mov_b32_e32 v3, 0x2002c
	global_atomic_add v1, v2, s[26:27]
	ds_write_b32 v3, v1
	v_mov_b32_e32 v3, 0x20000
	s_add_u32 s6, s26, 0x4800
	s_addc_u32 s7, s27, 0
	v_mov_b32_e32 v4, s6
	v_mov_b32_e32 v5, s7
	ds_write_b64 v3, v[4:5] offset:64
	s_add_u32 s6, s26, 0x4900
	s_addc_u32 s7, s27, 0
	v_mov_b32_e32 v6, s6
	v_mov_b32_e32 v7, s7
	ds_write_b64 v3, v[6:7] offset:72

; #define GRID_SYNC() do { xcd_barrier(xbar); } while (0)
; __global__ void __launch_bounds__(512) fwd_megakernel(KArgs a) {
;     ...
;         if (layer < 3) GRID_SYNC();
;     }
.LBB0_164:
	s_or_b64 exec, exec, s[0:1]
	s_and_saveexec_b64 s[0:1], s[96:97]
	v_mov_b32_e32 v0, 0x20000
	ds_read_b32 v1, v0 offset:40
	ds_read_b32 v2, v0 offset:56
	s_waitcnt lgkmcnt(0)
	v_add_u32_e32 v2, v2, v1
	ds_write_b32 v0, v2 offset:56
	s_waitcnt lgkmcnt(0)
	s_or_b64 exec, exec, s[0:1]
	s_waitcnt lgkmcnt(0)
	s_barrier

; __device__ __forceinline__ unsigned cvt_pk_bf16(float lo, float hi) { f32x2 v = {lo, hi}; bf16x2_t b = __builtin_convertvector(v, bf16x2_t); return __builtin_bit_cast(unsigned, b); }
;     __device__ __forceinline__ void operator()(const f32x4 (&acc)[2][2][4][2], const Unit& u, int wr, int wc, int fr, int fq) const {
;     ...
;                 if (MODE == 0 || MODE == 1) {
; #pragma unroll
;                     for (int bj = 0; bj < 2; ++bj) {
;                         const int hf = 2 * u.pn + bj;
;                         bf16_t* dst;
;                         if (split2) dst = ((hf & 1) ? O2 : O) + (size_t)row * ldc + (hf >> 1) * 128 + wc * 32 + 8 * fq;
;                         else dst = O + (size_t)row * ldc + hf * 128 + wc * 32 + 8 * fq;
;                         f32x4 v0 = acc[ai][bj][m][0] * sc, v1 = acc[ai][bj][m][1] * sc;
;                         if (MODE == 1) {
; #pragma unroll
;                             for (int e = 0; e < 4; ++e) { float a = fmaxf(v0[e], 0.f), b = fmaxf(v1[e], 0.f); v0[e] = a * a; v1[e] = b * b; }
;                         }
;                         u32x4 w; w.x = cvt_pk_bf16(v0[0], v0[1]); w.y = cvt_pk_bf16(v0[2], v0[3]); w.z = cvt_pk_bf16(v1[0], v1[1]); w.w = cvt_pk_bf16(v1[2], v1[3]);
;                         if (MODE == 1) asm volatile("global_store_dwordx4 %0, %1, off sc1\n\ts_nop 1" :: "v"(dst), "v"(w) : "memory");
;                         else *(u32x4*)dst = w;
.LBB0_485:
	v_mov_b32_e32 v214, 0x20000
	ds_read_b64 v[218:219], v214 offset:56
	s_waitcnt lgkmcnt(0)
	v_cmp_eq_u32_e32 vcc, v218, v219
	s_cbranch_vccnz .Lgw_ok_m0
	ds_read_b64 v[216:217], v214 offset:72
	ds_read_b32 v220, v214 offset:36
	v_mov_b32_e32 v215, 0
	s_waitcnt lgkmcnt(0)
	v_mul_lo_u32 v220, v220, v218
.Lgw_spin_m0:
	global_load_dword v219, v[216:217], off sc1
	v_add_u32_e32 v215, 1, v215
	s_waitcnt vmcnt(0)
	v_cmp_ge_u32_e32 vcc, v219, v220
	s_cbranch_vccnz .Lgw_done_m0
	v_cmp_lt_u32_e32 vcc, 0x40000, v215
	s_cbranch_vccnz .Lgw_done_m0
	s_sleep 2
	s_branch .Lgw_spin_m0
.Lgw_done_m0:
	ds_write_b32 v214, v218 offset:60

; #define PG8_LAS __attribute__((address_space(3)))
; __device__ __forceinline__ unsigned cvt_pk_bf16(float lo, float hi) { f32x2 v = {lo, hi}; bf16x2_t b = __builtin_convertvector(v, bf16x2_t); return __builtin_bit_cast(unsigned, b); }
;     __device__ __forceinline__ void epi_knorm(const f32x4 (&acc)[2][2][4][2], const Unit& u, int wr, int wc, int fr, int fq) const {
;     ...
;                 const int rowl = ai * HALF + wr * 64 + m * 16 + fr, row = u.pm * BM + rowl;
; #pragma unroll
;                 for (int bj = 0; bj < 2; ++bj) {
;                     const int hf = hf0 + bj;
;                     f32x4 v0 = acc[ai][bj][m][0] * sc[ai][m], v1 = acc[ai][bj][m][1] * sc[ai][m];
;                     if (bj == 0 ? isk0 : isk1) {
;                         const f32x4 t = *(const PG8_LAS f32x4*)(X + (rowl * 2 + bj) * 4);
;                         const float sk = __builtin_amdgcn_rsqf(((t[0] + t[1]) + (t[2] + t[3])) * (1.0f / 128.0f) + RMS_EPS_F);
;                         v0 = v0 * sk * g0; v1 = v1 * sk * g1;
; #pragma unroll
;                         for (int e = 0; e < 4; ++e) { cs[bj][e] += v0[e]; cs[bj][4 + e] += v1[e]; }
;                     }
;                     bf16_t* dst;
;                     if (split2) dst = ((hf & 1) ? O2 : O) + (size_t)row * ldc + (hf >> 1) * 128 + wc * 32 + 8 * fq;
;                     else dst = O + (size_t)row * ldc + hf * 128 + wc * 32 + 8 * fq;
;                     u32x4 w; w.x = cvt_pk_bf16(v0[0], v0[1]); w.y = cvt_pk_bf16(v0[2], v0[3]); w.z = cvt_pk_bf16(v1[0], v1[1]); w.w = cvt_pk_bf16(v1[2], v1[3]);
;                     *(u32x4*)dst = w;
;                 }
.LBB0_508:
	v_mov_b32_e32 v228, 0x20000
	ds_read_b64 v[236:237], v228 offset:56
	s_waitcnt lgkmcnt(0)
	v_cmp_eq_u32_e32 vcc, v236, v237
	s_cbranch_vccnz .Lgw_ok_m4
	ds_read_b64 v[230:231], v228 offset:72
	ds_read_b32 v238, v228 offset:36
	v_mov_b32_e32 v239, 0
	s_waitcnt lgkmcnt(0)
	v_mul_lo_u32 v238, v238, v236
.Lgw_spin_m4:
	global_load_dword v237, v[230:231], off sc1
	v_add_u32_e32 v239, 1, v239
	s_waitcnt vmcnt(0)
	v_cmp_ge_u32_e32 vcc, v237, v238
	s_cbranch_vccnz .Lgw_done_m4
	v_cmp_lt_u32_e32 vcc, 0x40000, v239
	s_cbranch_vccnz .Lgw_done_m4
	s_sleep 2
	s_branch .Lgw_spin_m4
.Lgw_done_m4:
	ds_write_b32 v228, v236 offset:60

; __device__ __forceinline__ unsigned xb_ld(unsigned* p)              { return __hip_atomic_load(p, __ATOMIC_RELAXED, __HIP_MEMORY_SCOPE_AGENT); }
; __device__ __forceinline__ unsigned xb_add(unsigned* p, unsigned v) { return __hip_atomic_fetch_add(p, v, __ATOMIC_RELAXED, __HIP_MEMORY_SCOPE_AGENT); }
; #define XB_SPIN(cond, bar) do { unsigned _sp = 0; while (cond) { __builtin_amdgcn_s_sleep(1); \
;     if ((++_sp & 255u) == 0u) { if (xb_ld(&(bar)[XB_TMO])) break; if (_sp > XB_SPIN_CAP) { atomicAdd(&(bar)[XB_TMO], 1u); break; } } } } while (0)
; __device__ __forceinline__ void xcd_barrier(const XcdBarrier& b) {
;     ...
;         const unsigned old = xb_add(&bar[XB_XSUB(b.x)], 1u);
;         const unsigned gen = old / nloc;
;         if (old + 1u == (gen + 1u) * nloc) {
;             __builtin_amdgcn_fence(__ATOMIC_RELEASE, "agent");
;             asm volatile("s_waitcnt vmcnt(0)" ::: "memory");
;             const unsigned og = xb_add(&bar[XB_TOP], 1u);
;             const unsigned tg = og / nx;
;             if (og + 1u == (tg + 1u) * nx) xb_add(&bar[XB_TOPGEN], 1u);
;             else XB_SPIN(xb_ld(&bar[XB_TOPGEN]) == tg, bar);
;             __builtin_amdgcn_fence(__ATOMIC_ACQUIRE, "agent");
;             xb_add(&bar[XB_XGEN(b.x)], 1u);
;             asm volatile("s_waitcnt vmcnt(0)" ::: "memory");
.LBB0_1030:
	s_andn2_saveexec_b64 s[4:5], s[4:5]
	s_cbranch_execz .LBB0_1050
	s_mov_b64 s[4:5], exec
	v_mov_b32_e32 v1, 0x20000
	ds_read_b32 v2, v1 offset:40
	s_waitcnt lgkmcnt(0)
	v_cmp_eq_u32_e32 vcc, 0, v2
	s_cbranch_vccnz .Lxb_gfull_3
	buffer_wbl2 sc1
	ds_read_b64 v[2:3], v1 offset:64
	s_waitcnt vmcnt(0) lgkmcnt(0)
	v_mov_b32_e32 v1, 1
	global_atomic_add v[2:3], v1, off
	s_branch .Lxb_local_3
.Lxb_gfull_3:
	buffer_wbl2 sc1
	s_waitcnt lgkmcnt(0)
	s_waitcnt vmcnt(0)
	v_mbcnt_lo_u32_b32 v1, s4, 0
	v_mbcnt_hi_u32_b32 v1, s5, v1
	v_cmp_eq_u32_e32 vcc, 0, v1
	s_and_saveexec_b64 s[6:7], vcc
	s_cbranch_execz .LBB0_1033
	s_bcnt1_i32_b64 s4, s[4:5]
	v_mov_b32_e32 v2, s4
	v_readlane_b32 s4, v253, 42
	v_readlane_b32 s5, v253, 43
	s_nop 4
	global_atomic_add v2, v181, v2, s[4:5] sc0

; #define GRID_SYNC() do { xcd_barrier(xbar); } while (0)
; __global__ void __launch_bounds__(512) fwd_megakernel(KArgs a) {
;     ...
;             if (rep == 0) {
;                 GRID_SYNC();
;                 pg8::Gemm g{XB, (const bf16*)(wm + W_MLP_IN), TOK, 4096, 1024}; pg8::RevOrder S; S.init(TOK, 4096, G, bx);
;                 pg8::EpiGen<1> E{nullptr, 0, 0.f, (bf16*)(ws + WS_H), 4096, nullptr, nullptr, 0, nullptr, nullptr, nullptr, nullptr, nullptr, nullptr, 0, (pg8::PG8_LAS_F)(lds + 131072 + 256)};
;                 pg8::gemm_phase<pg8::EpiGen<1>, pg8::RevOrder, true, true>(lds, g, S, E);
.LBB0_1050:
	s_or_b64 exec, exec, s[0:1]
	s_and_saveexec_b64 s[0:1], s[96:97]
	v_mov_b32_e32 v0, 0x20000
	ds_read_b32 v1, v0 offset:40
	ds_read_b32 v2, v0 offset:48
	s_waitcnt lgkmcnt(0)
	v_add_u32_e32 v2, v2, v1
	ds_write_b32 v0, v2 offset:48
	s_waitcnt lgkmcnt(0)
	s_or_b64 exec, exec, s[0:1]
	v_readlane_b32 s0, v254, 20
	v_mov_b32_e32 v6, v202
	v_readlane_b32 s1, v254, 21
	s_waitcnt lgkmcnt(0)
	s_barrier
	s_andn2_b64 vcc, exec, s[0:1]
	v_readfirstlane_b32 s4, v6
	s_cbranch_vccnz .LBB0_1074
	v_readlane_b32 s0, v254, 27
	v_readlane_b32 s1, v254, 28
	s_andn2_b64 vcc, exec, s[0:1]
	s_cbranch_vccnz .LBB0_1074
	v_readlane_b32 s0, v254, 23
	v_readlane_b32 s1, v254, 24
	s_andn2_b64 vcc, exec, s[0:1]
	v_readlane_b32 s0, v254, 30
	s_cbranch_vccnz .LBB0_1054
	v_readlane_b32 s0, v254, 29

; __device__ __forceinline__ unsigned cvt_pk_bf16(float lo, float hi) { f32x2 v = {lo, hi}; bf16x2_t b = __builtin_convertvector(v, bf16x2_t); return __builtin_bit_cast(unsigned, b); }
;     __device__ __forceinline__ void operator()(const f32x4 (&acc)[2][2][4][2], const Unit& u, int wr, int wc, int fr, int fq) const {
;     ...
;                 if (MODE == 0 || MODE == 1) {
; #pragma unroll
;                     for (int bj = 0; bj < 2; ++bj) {
;                         const int hf = 2 * u.pn + bj;
;                         bf16_t* dst;
;                         if (split2) dst = ((hf & 1) ? O2 : O) + (size_t)row * ldc + (hf >> 1) * 128 + wc * 32 + 8 * fq;
;                         else dst = O + (size_t)row * ldc + hf * 128 + wc * 32 + 8 * fq;
;                         f32x4 v0 = acc[ai][bj][m][0] * sc, v1 = acc[ai][bj][m][1] * sc;
;                         if (MODE == 1) {
; #pragma unroll
;                             for (int e = 0; e < 4; ++e) { float a = fmaxf(v0[e], 0.f), b = fmaxf(v1[e], 0.f); v0[e] = a * a; v1[e] = b * b; }
;                         }
;                         u32x4 w; w.x = cvt_pk_bf16(v0[0], v0[1]); w.y = cvt_pk_bf16(v0[2], v0[3]); w.z = cvt_pk_bf16(v1[0], v1[1]); w.w = cvt_pk_bf16(v1[2], v1[3]);
;                         if (MODE == 1) asm volatile("global_store_dwordx4 %0, %1, off sc1\n\ts_nop 1" :: "v"(dst), "v"(w) : "memory");
;                         else *(u32x4*)dst = w;
;                     }
.LBB0_1070:
	v_mov_b32_e32 v246, 0x20000
	ds_read_b64 v[250:251], v246 offset:48
	s_waitcnt lgkmcnt(0)
	v_cmp_eq_u32_e32 vcc, v250, v251
	s_cbranch_vccnz .Lgw_ok_m1
	ds_read_b64 v[248:249], v246 offset:64
	ds_read_b32 v247, v246 offset:36
	v_mov_b32_e32 v245, 0
	s_waitcnt lgkmcnt(0)
	v_mul_lo_u32 v247, v247, v250
.Lgw_spin_m1:
	global_load_dword v251, v[248:249], off sc1
	v_add_u32_e32 v245, 1, v245
	s_waitcnt vmcnt(0)
	v_cmp_ge_u32_e32 vcc, v251, v247
	s_cbranch_vccnz .Lgw_done_m1
	v_cmp_lt_u32_e32 vcc, 0x40000, v245
	s_cbranch_vccnz .Lgw_done_m1
	s_sleep 2
	s_branch .Lgw_spin_m1
.Lgw_done_m1:
	ds_write_b32 v246, v250 offset:52

; __device__ __forceinline__ unsigned xb_ld(unsigned* p)              { return __hip_atomic_load(p, __ATOMIC_RELAXED, __HIP_MEMORY_SCOPE_AGENT); }
; __device__ __forceinline__ unsigned xb_add(unsigned* p, unsigned v) { return __hip_atomic_fetch_add(p, v, __ATOMIC_RELAXED, __HIP_MEMORY_SCOPE_AGENT); }
; #define XB_SPIN(cond, bar) do { unsigned _sp = 0; while (cond) { __builtin_amdgcn_s_sleep(1); \
;     if ((++_sp & 255u) == 0u) { if (xb_ld(&(bar)[XB_TMO])) break; if (_sp > XB_SPIN_CAP) { atomicAdd(&(bar)[XB_TMO], 1u); break; } } } } while (0)
; __device__ __forceinline__ void xcd_barrier(const XcdBarrier& b) {
;     ...
;         const unsigned old = xb_add(&bar[XB_XSUB(b.x)], 1u);
;         const unsigned gen = old / nloc;
;         if (old + 1u == (gen + 1u) * nloc) {
;             __builtin_amdgcn_fence(__ATOMIC_RELEASE, "agent");
;             asm volatile("s_waitcnt vmcnt(0)" ::: "memory");
;             const unsigned og = xb_add(&bar[XB_TOP], 1u);
;             const unsigned tg = og / nx;
;             if (og + 1u == (tg + 1u) * nx) xb_add(&bar[XB_TOPGEN], 1u);
;             else XB_SPIN(xb_ld(&bar[XB_TOPGEN]) == tg, bar);
;             __builtin_amdgcn_fence(__ATOMIC_ACQUIRE, "agent");
;             xb_add(&bar[XB_XGEN(b.x)], 1u);
;             asm volatile("s_waitcnt vmcnt(0)" ::: "memory");
.LBB0_1158:
	s_andn2_saveexec_b64 s[4:5], s[4:5]
	s_cbranch_execz .LBB0_164
	s_mov_b64 s[4:5], exec
	v_mov_b32_e32 v1, 0x20000
	ds_read_b32 v2, v1 offset:40
	s_waitcnt lgkmcnt(0)
	v_cmp_eq_u32_e32 vcc, 0, v2
	s_cbranch_vccnz .Lxb_gfull_5
	ds_read_b64 v[2:3], v1 offset:72
	s_waitcnt vmcnt(0) lgkmcnt(0)
	v_mov_b32_e32 v1, 1
	global_atomic_add v[2:3], v1, off
	s_branch .Lxb_local_5
